# v42: lever 4 - one static priority raise for waves 4..7 during the attention-item loop (reset at loop exit)
# baseline (speedup 1.0000x reference)
.LBB0_1333:
	v_writelane_b32 v255, s30, 20
	v_readlane_b32 s0, v254, 31
	v_readlane_b32 s1, v254, 32
	v_writelane_b32 v255, s31, 21
	v_writelane_b32 v255, s29, 22
	v_writelane_b32 v255, s28, 23
	v_writelane_b32 v255, s60, 24
	v_mov_b32_e32 v185, 0x3727c5ac
	v_mov_b32_e32 v188, 0x1000
	v_writelane_b32 v255, s61, 25
	v_mov_b32_e32 v186, 0x2000
	v_mov_b32_e32 v187, 0xe00
	s_andn2_b64 vcc, exec, s[0:1]
	s_cbranch_vccnz .LBB0_1397
	v_readfirstlane_b32 s32, v173
	s_nop 0
	s_lshr_b32 s32, s32, 8
	s_cmp_eq_u32 s32, 1
	s_cbranch_scc0 .Lat_prio_skip
	s_setprio 1
.Lat_prio_skip:
	s_add_u32 s54, s64, 0x12b00000
	s_addc_u32 s88, s65, 0
	s_add_u32 s44, s64, 0x13300000
	s_addc_u32 s87, s65, 0
	s_add_u32 s47, s64, 0x12f00000
	v_readlane_b32 s0, v254, 1
	s_addc_u32 s81, s65, 0
	s_mov_b32 s80, s0
	v_readlane_b32 s1, v254, 2
	s_branch .LBB0_1336

.LBB0_1397:
	s_setprio 0
	v_readlane_b32 s66, v254, 3
	v_readlane_b32 s67, v254, 4
	s_load_dword s69, s[66:67], 0xe8
	s_load_dwordx2 s[62:63], s[66:67], 0xe0
	v_readlane_b32 s60, v255, 24
	v_readlane_b32 s30, v255, 20
	s_mov_b64 s[0:1], 0
	s_movk_i32 s68, 0x7f
	s_mov_b32 s74, 0x7fffffe0
	s_mov_b32 s75, 0xd700000
	s_mov_b32 s80, 0x800000
	s_mov_b32 s86, 0x3e38aa3b
	s_movk_i32 s81, 0xf00
	s_mov_b32 s87, 0x12f00000
	s_movk_i32 s88, 0xc00
	s_mov_b64 s[90:91], 0x800
	s_movk_i32 s94, 0x51
	s_movk_i32 s95, 0xb1
	s_movk_i32 s56, 0x1600
	v_readlane_b32 s57, v254, 62
	v_readlane_b32 s58, v254, 63
	v_readlane_b32 s59, v255, 16
	v_readlane_b32 s61, v255, 25
	v_readlane_b32 s48, v254, 40
	v_readlane_b32 s28, v255, 23
	v_readlane_b32 s29, v255, 22
	v_readlane_b32 s31, v255, 21
	v_mov_b32_e32 v192, v187
	v_mov_b32_e32 v187, v186
	v_mov_b32_e32 v186, v188
	v_mov_b32_e32 v188, 1
	v_mov_b32_e32 v193, 0x12b00000
	v_mov_b32_e32 v194, 0x12700000
